# E_KV GEMM epilogue: destination selected once per tile, permlane16_swap pairs -> 16 dwordx4 stores per lane instead of 32 dwordx2
# speedup vs baseline: 1.0174x; 1.0046x over previous
.LBB0_1086:
	s_and_b64 vcc, exec, s[2:3]
	s_cbranch_vccz .LBB0_1216
	s_and_b64 s[2:3], s[8:9], exec
	v_readlane_b32 s2, v255, 28
	s_waitcnt vmcnt(0)
	v_add_u32_e32 v132, s45, v225
	v_or_b32_e32 v130, s6, v224
	v_readlane_b32 s3, v255, 29
	v_ashrrev_i32_e32 v133, 31, v132
	v_ashrrev_i32_e32 v130, 1, v130
	s_cselect_b32 s3, 0, s3
	s_cselect_b32 s2, 0, s2
	v_lshlrev_b32_e32 v0, 2, v223
	v_lshlrev_b64 v[136:137], 11, v[132:133]
	v_and_b32_e32 v131, 64, v224
	v_and_b32_e32 v130, 0xffffffc0, v130
	v_and_or_b32 v0, v224, 64, v0
	v_cmp_ne_u32_e32 vcc, 0, v131
	v_ashrrev_i32_e32 v131, 31, v130
	v_lshl_add_u64 v[134:135], s[2:3], 0, v[136:137]
	v_lshl_add_u64 v[134:135], v[130:131], 1, v[134:135]
	v_lshlrev_b32_e32 v0, 1, v0
	v_lshl_add_u64 v[136:137], s[42:43], 0, v[136:137]
	v_lshl_add_u64 v[136:137], v[130:131], 1, v[136:137]
	s_movk_i32 s8, 0xff80
	s_mov_b32 s9, -1
	v_lshl_add_u64 v[134:135], v[134:135], 0, s[8:9]
	v_cndmask_b32_e32 v132, v136, v134, vcc
	v_cndmask_b32_e32 v133, v137, v135, vcc
	v_lshl_add_u64 v[132:133], v[132:133], 0, v[0:1]
	v_and_b32_e32 v134, 1, v223
	v_mul_u32_u24_e32 v134, 24, v134
	v_mov_b32_e32 v135, 0
	v_lshl_add_u64 v[132:133], v[132:133], 0, v[134:135]
	s_mov_b32 s4, 0x8000
	s_mov_b32 s5, 0
	v_cvt_pk_bf16_f32 v126, v126, v127
	v_cvt_pk_bf16_f32 v127, v128, v129
	v_cvt_pk_bf16_f32 v128, v122, v123
	v_cvt_pk_bf16_f32 v129, v124, v125
	s_nop 1
	v_permlane16_swap_b32_e32 v126, v128
	v_permlane16_swap_b32_e32 v127, v129
	global_store_dwordx4 v[132:133], v[126:129], off
	v_cvt_pk_bf16_f32 v118, v118, v119
	v_cvt_pk_bf16_f32 v119, v120, v121
	v_cvt_pk_bf16_f32 v120, v114, v115
	v_cvt_pk_bf16_f32 v121, v116, v117
	s_nop 1
	v_permlane16_swap_b32_e32 v118, v120
	v_permlane16_swap_b32_e32 v119, v121
	global_store_dwordx4 v[132:133], v[118:121], off offset:64
	v_lshl_add_u64 v[132:133], v[132:133], 0, s[4:5]
	v_cvt_pk_bf16_f32 v110, v110, v111
	v_cvt_pk_bf16_f32 v111, v112, v113
	v_cvt_pk_bf16_f32 v112, v106, v107
	v_cvt_pk_bf16_f32 v113, v108, v109
	s_nop 1
	v_permlane16_swap_b32_e32 v110, v112
	v_permlane16_swap_b32_e32 v111, v113
	global_store_dwordx4 v[132:133], v[110:113], off
	v_cvt_pk_bf16_f32 v102, v102, v103
	v_cvt_pk_bf16_f32 v103, v104, v105
	v_cvt_pk_bf16_f32 v104, v98, v99
	v_cvt_pk_bf16_f32 v105, v100, v101
	s_nop 1
	v_permlane16_swap_b32_e32 v102, v104
	v_permlane16_swap_b32_e32 v103, v105
	global_store_dwordx4 v[132:133], v[102:105], off offset:64
	v_lshl_add_u64 v[132:133], v[132:133], 0, s[4:5]
	v_cvt_pk_bf16_f32 v94, v94, v95
	v_cvt_pk_bf16_f32 v95, v96, v97
	v_cvt_pk_bf16_f32 v96, v90, v91
	v_cvt_pk_bf16_f32 v97, v92, v93
	s_nop 1
	v_permlane16_swap_b32_e32 v94, v96
	v_permlane16_swap_b32_e32 v95, v97
	global_store_dwordx4 v[132:133], v[94:97], off
	v_cvt_pk_bf16_f32 v86, v86, v87
	v_cvt_pk_bf16_f32 v87, v88, v89
	v_cvt_pk_bf16_f32 v88, v82, v83
	v_cvt_pk_bf16_f32 v89, v84, v85
	s_nop 1
	v_permlane16_swap_b32_e32 v86, v88
	v_permlane16_swap_b32_e32 v87, v89
	global_store_dwordx4 v[132:133], v[86:89], off offset:64
	v_lshl_add_u64 v[132:133], v[132:133], 0, s[4:5]
	v_cvt_pk_bf16_f32 v78, v78, v79
	v_cvt_pk_bf16_f32 v79, v80, v81
	v_cvt_pk_bf16_f32 v80, v74, v75
	v_cvt_pk_bf16_f32 v81, v76, v77
	s_nop 1
	v_permlane16_swap_b32_e32 v78, v80
	v_permlane16_swap_b32_e32 v79, v81
	global_store_dwordx4 v[132:133], v[78:81], off
	v_cvt_pk_bf16_f32 v70, v70, v71
	v_cvt_pk_bf16_f32 v71, v72, v73
	v_cvt_pk_bf16_f32 v72, v66, v67
	v_cvt_pk_bf16_f32 v73, v68, v69
	s_nop 1
	v_permlane16_swap_b32_e32 v70, v72
	v_permlane16_swap_b32_e32 v71, v73
	global_store_dwordx4 v[132:133], v[70:73], off offset:64
	v_lshl_add_u64 v[132:133], v[132:133], 0, s[4:5]
	v_cvt_pk_bf16_f32 v62, v62, v63
	v_cvt_pk_bf16_f32 v63, v64, v65
	v_cvt_pk_bf16_f32 v64, v58, v59
	v_cvt_pk_bf16_f32 v65, v60, v61
	s_nop 1
	v_permlane16_swap_b32_e32 v62, v64
	v_permlane16_swap_b32_e32 v63, v65
	global_store_dwordx4 v[132:133], v[62:65], off
	v_cvt_pk_bf16_f32 v54, v54, v55
	v_cvt_pk_bf16_f32 v55, v56, v57
	v_cvt_pk_bf16_f32 v56, v50, v51
	v_cvt_pk_bf16_f32 v57, v52, v53
	s_nop 1
	v_permlane16_swap_b32_e32 v54, v56
	v_permlane16_swap_b32_e32 v55, v57
	global_store_dwordx4 v[132:133], v[54:57], off offset:64
	v_lshl_add_u64 v[132:133], v[132:133], 0, s[4:5]
	v_cvt_pk_bf16_f32 v46, v46, v47
	v_cvt_pk_bf16_f32 v47, v48, v49
	v_cvt_pk_bf16_f32 v48, v42, v43
	v_cvt_pk_bf16_f32 v49, v44, v45
	s_nop 1
	v_permlane16_swap_b32_e32 v46, v48
	v_permlane16_swap_b32_e32 v47, v49
	global_store_dwordx4 v[132:133], v[46:49], off
	v_cvt_pk_bf16_f32 v34, v34, v35
	v_cvt_pk_bf16_f32 v35, v36, v37
	v_cvt_pk_bf16_f32 v36, v30, v31
	v_cvt_pk_bf16_f32 v37, v32, v33
	s_nop 1
	v_permlane16_swap_b32_e32 v34, v36
	v_permlane16_swap_b32_e32 v35, v37
	global_store_dwordx4 v[132:133], v[34:37], off offset:64
	v_lshl_add_u64 v[132:133], v[132:133], 0, s[4:5]
	v_cvt_pk_bf16_f32 v38, v38, v39
	v_cvt_pk_bf16_f32 v39, v40, v41
	v_cvt_pk_bf16_f32 v40, v26, v27
	v_cvt_pk_bf16_f32 v41, v28, v29
	s_nop 1
	v_permlane16_swap_b32_e32 v38, v40
	v_permlane16_swap_b32_e32 v39, v41
	global_store_dwordx4 v[132:133], v[38:41], off
	v_cvt_pk_bf16_f32 v22, v22, v23
	v_cvt_pk_bf16_f32 v23, v24, v25
	v_cvt_pk_bf16_f32 v24, v18, v19
	v_cvt_pk_bf16_f32 v25, v20, v21
	s_nop 1
	v_permlane16_swap_b32_e32 v22, v24
	v_permlane16_swap_b32_e32 v23, v25
	global_store_dwordx4 v[132:133], v[22:25], off offset:64
	v_lshl_add_u64 v[132:133], v[132:133], 0, s[4:5]
	v_cvt_pk_bf16_f32 v14, v14, v15
	v_cvt_pk_bf16_f32 v15, v16, v17
	v_cvt_pk_bf16_f32 v16, v10, v11
	v_cvt_pk_bf16_f32 v17, v12, v13
	s_nop 1
	v_permlane16_swap_b32_e32 v14, v16
	v_permlane16_swap_b32_e32 v15, v17
	global_store_dwordx4 v[132:133], v[14:17], off
	v_cvt_pk_bf16_f32 v6, v6, v7
	v_cvt_pk_bf16_f32 v7, v8, v9
	v_cvt_pk_bf16_f32 v8, v2, v3
	v_cvt_pk_bf16_f32 v9, v4, v5
	s_nop 1
	v_permlane16_swap_b32_e32 v6, v8
	v_permlane16_swap_b32_e32 v7, v9
	global_store_dwordx4 v[132:133], v[6:9], off offset:64
